# P10 epilogue: 16 residual loads of a tile issued together at epilogue top, counted waits
# baseline (speedup 1.0000x reference)
.LBB0_1382:
	v_lshl_add_u32 v144, s42, 8, v154
	v_lshl_or_b32 v146, s40, 8, v156
	v_ashrrev_i32_e32 v145, 31, v144
	v_ashrrev_i32_e32 v147, 31, v146
	v_lshlrev_b32_e32 v236, 12, v144
	v_lshl_add_u32 v236, v146, 1, v236
	v_add_u32_e32 v237, 0x10000, v236
	v_add_u32_e32 v238, 0x20000, v236
	v_add_u32_e32 v239, 0x30000, v236
	v_add_u32_e32 v240, 0x80000, v236
	v_add_u32_e32 v241, 0x90000, v236
	v_add_u32_e32 v242, 0xa0000, v236
	v_add_u32_e32 v243, 0xb0000, v236
	global_load_dwordx4 v[172:175], v236, s[12:13]
	global_load_dwordx4 v[176:179], v236, s[12:13] offset:256
	global_load_dwordx4 v[180:183], v237, s[12:13]
	global_load_dwordx4 v[184:187], v237, s[12:13] offset:256
	global_load_dwordx4 v[188:191], v238, s[12:13]
	global_load_dwordx4 v[192:195], v238, s[12:13] offset:256
	global_load_dwordx4 v[196:199], v239, s[12:13]
	global_load_dwordx4 v[200:203], v239, s[12:13] offset:256
	global_load_dwordx4 v[204:207], v240, s[12:13]
	global_load_dwordx4 v[208:211], v240, s[12:13] offset:256
	global_load_dwordx4 v[212:215], v241, s[12:13]
	global_load_dwordx4 v[216:219], v241, s[12:13] offset:256
	global_load_dwordx4 v[220:223], v242, s[12:13]
	global_load_dwordx4 v[224:227], v242, s[12:13] offset:256
	global_load_dwordx4 v[228:231], v243, s[12:13]
	global_load_dwordx4 v[232:235], v243, s[12:13] offset:256
	v_lshlrev_b64 v[148:149], 12, v[144:145]
	v_lshl_add_u64 v[148:149], s[12:13], 0, v[148:149]
	v_lshlrev_b64 v[152:153], 1, v[146:147]
	v_lshl_add_u64 v[146:147], v[148:149], 0, v[152:153]
	v_or_b32_e32 v164, 16, v144
	v_ashrrev_i32_e32 v165, 31, v164
	v_lshlrev_b64 v[164:165], 12, v[164:165]
	v_lshl_add_u64 v[164:165], s[12:13], 0, v[164:165]
	v_lshl_add_u64 v[168:169], v[164:165], 0, v[152:153]
	v_or_b32_e32 v164, 32, v144
	v_ashrrev_i32_e32 v165, 31, v164
	v_lshlrev_b64 v[164:165], 12, v[164:165]
	v_lshl_add_u64 v[164:165], s[12:13], 0, v[164:165]
	v_lshl_add_u64 v[170:171], v[164:165], 0, v[152:153]
	s_waitcnt vmcnt(15)
	v_lshlrev_b32_e32 v160, 16, v172
	v_and_b32_e32 v161, 0xffff0000, v172
	v_lshlrev_b32_e32 v148, 16, v173
	v_and_b32_e32 v149, 0xffff0000, v173
	v_lshlrev_b32_e32 v162, 16, v174
	v_and_b32_e32 v163, 0xffff0000, v174
	v_lshlrev_b32_e32 v150, 16, v175
	v_and_b32_e32 v151, 0xffff0000, v175
	v_pk_add_f32 v[126:127], v[126:127], v[148:149]
	v_pk_add_f32 v[124:125], v[124:125], v[160:161]
	v_pk_add_f32 v[122:123], v[122:123], v[150:151]
	v_pk_add_f32 v[120:121], v[120:121], v[162:163]
	v_cvt_pk_bf16_f32 v148, v124, v125
	v_cvt_pk_bf16_f32 v149, v126, v127
	s_nop 0
	v_cvt_pk_bf16_f32 v150, v120, v121
	v_cvt_pk_bf16_f32 v151, v122, v123
	s_nop 0
	global_store_dwordx4 v[146:147], v[148:151], off
	s_waitcnt vmcnt(15)
	s_nop 0
	v_lshlrev_b32_e32 v148, 16, v176
	v_and_b32_e32 v149, 0xffff0000, v176
	v_lshlrev_b32_e32 v150, 16, v177
	v_and_b32_e32 v151, 0xffff0000, v177
	v_lshlrev_b32_e32 v160, 16, v178
	v_and_b32_e32 v161, 0xffff0000, v178
	v_lshlrev_b32_e32 v162, 16, v179
	v_and_b32_e32 v163, 0xffff0000, v179
	v_pk_add_f32 v[114:115], v[114:115], v[150:151]
	v_pk_add_f32 v[148:149], v[112:113], v[148:149]
	v_pk_add_f32 v[112:113], v[110:111], v[162:163]
	v_pk_add_f32 v[150:151], v[108:109], v[160:161]
	v_cvt_pk_bf16_f32 v108, v148, v149
	v_cvt_pk_bf16_f32 v109, v114, v115
	s_nop 0
	v_cvt_pk_bf16_f32 v110, v150, v151
	v_cvt_pk_bf16_f32 v111, v112, v113
	v_mul_f32_e32 v113, v113, v113
	global_store_dwordx4 v[146:147], v[108:111], off offset:256
	v_fmac_f32_e32 v113, v112, v112
	s_waitcnt vmcnt(15)
	v_lshlrev_b32_e32 v110, 16, v180
	v_and_b32_e32 v111, 0xffff0000, v180
	v_lshlrev_b32_e32 v108, 16, v181
	v_and_b32_e32 v109, 0xffff0000, v181
	v_lshlrev_b32_e32 v160, 16, v182
	v_and_b32_e32 v161, 0xffff0000, v182
	v_lshlrev_b32_e32 v162, 16, v183
	v_and_b32_e32 v163, 0xffff0000, v183
	v_pk_add_f32 v[108:109], v[118:119], v[108:109]
	v_pk_add_f32 v[110:111], v[116:117], v[110:111]
	v_pk_add_f32 v[106:107], v[106:107], v[162:163]
	v_pk_add_f32 v[104:105], v[104:105], v[160:161]
	v_cvt_pk_bf16_f32 v116, v110, v111
	v_cvt_pk_bf16_f32 v117, v108, v109
	s_nop 0
	v_cvt_pk_bf16_f32 v118, v104, v105
	v_cvt_pk_bf16_f32 v119, v106, v107
	s_nop 0
	global_store_dwordx4 v[168:169], v[116:119], off
	s_waitcnt vmcnt(15)
	s_nop 0
	v_lshlrev_b32_e32 v118, 16, v184
	v_and_b32_e32 v119, 0xffff0000, v184
	v_lshlrev_b32_e32 v116, 16, v185
	v_and_b32_e32 v117, 0xffff0000, v185
	v_lshlrev_b32_e32 v160, 16, v186
	v_and_b32_e32 v161, 0xffff0000, v186
	v_lshlrev_b32_e32 v162, 16, v187
	v_and_b32_e32 v163, 0xffff0000, v187
	v_pk_add_f32 v[116:117], v[98:99], v[116:117]
	v_pk_add_f32 v[118:119], v[96:97], v[118:119]
	v_pk_add_f32 v[94:95], v[94:95], v[162:163]
	v_pk_add_f32 v[98:99], v[92:93], v[160:161]
	v_cvt_pk_bf16_f32 v160, v118, v119
	v_cvt_pk_bf16_f32 v161, v116, v117
	s_nop 0
	v_cvt_pk_bf16_f32 v162, v98, v99
	v_cvt_pk_bf16_f32 v163, v94, v95
	s_waitcnt vmcnt(14)
	v_lshlrev_b32_e32 v96, 16, v188
	global_store_dwordx4 v[168:169], v[160:163], off offset:256
	v_and_b32_e32 v97, 0xffff0000, v188
	v_lshlrev_b32_e32 v92, 16, v189
	v_and_b32_e32 v93, 0xffff0000, v189
	v_lshlrev_b32_e32 v160, 16, v190
	v_and_b32_e32 v161, 0xffff0000, v190
	v_lshlrev_b32_e32 v162, 16, v191
	v_and_b32_e32 v163, 0xffff0000, v191
	v_pk_add_f32 v[92:93], v[102:103], v[92:93]
	v_pk_add_f32 v[96:97], v[100:101], v[96:97]
	v_pk_add_f32 v[90:91], v[90:91], v[162:163]
	v_pk_add_f32 v[88:89], v[88:89], v[160:161]
	v_cvt_pk_bf16_f32 v100, v96, v97
	v_cvt_pk_bf16_f32 v101, v92, v93
	v_or_b32_e32 v164, 48, v144
	v_cvt_pk_bf16_f32 v102, v88, v89
	v_cvt_pk_bf16_f32 v103, v90, v91
	v_ashrrev_i32_e32 v165, 31, v164
	v_lshlrev_b64 v[164:165], 12, v[164:165]
	v_lshl_add_u64 v[164:165], s[12:13], 0, v[164:165]
	v_lshl_add_u64 v[152:153], v[164:165], 0, v[152:153]
	global_store_dwordx4 v[170:171], v[100:103], off
	v_lshl_add_u64 v[168:169], v[146:147], 0, s[16:17]
	s_waitcnt vmcnt(15)
	v_lshlrev_b32_e32 v102, 16, v192
	v_and_b32_e32 v103, 0xffff0000, v192
	v_lshlrev_b32_e32 v100, 16, v193
	v_and_b32_e32 v101, 0xffff0000, v193
	v_lshlrev_b32_e32 v160, 16, v194
	v_and_b32_e32 v161, 0xffff0000, v194
	v_lshlrev_b32_e32 v162, 16, v195
	v_and_b32_e32 v163, 0xffff0000, v195
	v_pk_add_f32 v[100:101], v[82:83], v[100:101]
	v_pk_add_f32 v[102:103], v[80:81], v[102:103]
	v_pk_add_f32 v[78:79], v[78:79], v[162:163]
	v_pk_add_f32 v[82:83], v[76:77], v[160:161]
	v_cvt_pk_bf16_f32 v160, v102, v103
	v_cvt_pk_bf16_f32 v161, v100, v101
	s_nop 0
	v_cvt_pk_bf16_f32 v162, v82, v83
	v_cvt_pk_bf16_f32 v163, v78, v79
	s_waitcnt vmcnt(14)
	v_lshlrev_b32_e32 v80, 16, v196
	global_store_dwordx4 v[170:171], v[160:163], off offset:256
	v_and_b32_e32 v81, 0xffff0000, v196
	v_lshlrev_b32_e32 v76, 16, v197
	v_and_b32_e32 v77, 0xffff0000, v197
	v_lshlrev_b32_e32 v160, 16, v198
	v_and_b32_e32 v161, 0xffff0000, v198
	v_lshlrev_b32_e32 v162, 16, v199
	v_and_b32_e32 v163, 0xffff0000, v199
	v_pk_add_f32 v[76:77], v[86:87], v[76:77]
	v_pk_add_f32 v[80:81], v[84:85], v[80:81]
	v_pk_add_f32 v[74:75], v[74:75], v[162:163]
	v_pk_add_f32 v[72:73], v[72:73], v[160:161]
	v_cvt_pk_bf16_f32 v84, v80, v81
	v_cvt_pk_bf16_f32 v85, v76, v77
	v_add_co_u32_e32 v164, vcc, s60, v146
	v_cvt_pk_bf16_f32 v86, v72, v73
	v_cvt_pk_bf16_f32 v87, v74, v75
	s_nop 0
	v_addc_co_u32_e32 v165, vcc, 0, v147, vcc
	global_store_dwordx4 v[152:153], v[84:87], off
	s_waitcnt vmcnt(15)
	s_nop 0
	v_lshlrev_b32_e32 v84, 16, v200
	v_and_b32_e32 v85, 0xffff0000, v200
	v_lshlrev_b32_e32 v86, 16, v201
	v_and_b32_e32 v87, 0xffff0000, v201
	v_lshlrev_b32_e32 v160, 16, v202
	v_and_b32_e32 v161, 0xffff0000, v202
	v_lshlrev_b32_e32 v162, 16, v203
	v_and_b32_e32 v163, 0xffff0000, v203
	v_pk_add_f32 v[70:71], v[70:71], v[86:87]
	v_pk_add_f32 v[68:69], v[68:69], v[84:85]
	v_pk_add_f32 v[66:67], v[66:67], v[162:163]
	v_pk_add_f32 v[64:65], v[64:65], v[160:161]
	v_cvt_pk_bf16_f32 v84, v68, v69
	v_cvt_pk_bf16_f32 v85, v70, v71
	s_nop 0
	v_cvt_pk_bf16_f32 v86, v64, v65
	v_cvt_pk_bf16_f32 v87, v66, v67
	s_nop 0
	global_store_dwordx4 v[152:153], v[84:87], off offset:256
	s_waitcnt vmcnt(15)
	v_lshlrev_b32_e32 v152, 16, v206
	v_lshlrev_b32_e32 v84, 16, v204
	v_and_b32_e32 v85, 0xffff0000, v204
	v_lshlrev_b32_e32 v86, 16, v205
	v_and_b32_e32 v87, 0xffff0000, v205
	v_and_b32_e32 v153, 0xffff0000, v206
	v_lshlrev_b32_e32 v160, 16, v207
	v_and_b32_e32 v161, 0xffff0000, v207
	v_pk_add_f32 v[62:63], v[62:63], v[86:87]
	v_pk_add_f32 v[60:61], v[60:61], v[84:85]
	v_pk_add_f32 v[58:59], v[58:59], v[160:161]
	v_pk_add_f32 v[56:57], v[56:57], v[152:153]
	v_cvt_pk_bf16_f32 v84, v60, v61
	v_cvt_pk_bf16_f32 v85, v62, v63
	v_add_co_u32_e32 v152, vcc, s61, v146
	v_cvt_pk_bf16_f32 v86, v56, v57
	v_cvt_pk_bf16_f32 v87, v58, v59
	s_nop 0
	v_addc_co_u32_e32 v153, vcc, 0, v147, vcc
	global_store_dwordx4 v[164:165], v[84:87], off
	s_waitcnt vmcnt(15)
	s_nop 0
	v_lshlrev_b32_e32 v84, 16, v208
	v_and_b32_e32 v85, 0xffff0000, v208
	v_lshlrev_b32_e32 v86, 16, v209
	v_and_b32_e32 v87, 0xffff0000, v209
	v_lshlrev_b32_e32 v160, 16, v210
	v_and_b32_e32 v161, 0xffff0000, v210
	v_lshlrev_b32_e32 v162, 16, v211
	v_and_b32_e32 v163, 0xffff0000, v211
	v_pk_add_f32 v[54:55], v[54:55], v[86:87]
	v_pk_add_f32 v[84:85], v[52:53], v[84:85]
	v_pk_add_f32 v[46:47], v[46:47], v[162:163]
	v_pk_add_f32 v[52:53], v[44:45], v[160:161]
	v_cvt_pk_bf16_f32 v160, v84, v85
	v_cvt_pk_bf16_f32 v161, v54, v55
	v_lshl_add_u64 v[86:87], v[146:147], 0, s[20:21]
	v_cvt_pk_bf16_f32 v162, v52, v53
	v_cvt_pk_bf16_f32 v163, v46, v47
	s_waitcnt vmcnt(14)
	v_lshlrev_b32_e32 v44, 16, v213
	global_store_dwordx4 v[168:169], v[160:163], off offset:256
	v_and_b32_e32 v45, 0xffff0000, v213
	v_and_b32_e32 v165, 0xffff0000, v215
	v_lshlrev_b32_e32 v160, 16, v212
	v_and_b32_e32 v161, 0xffff0000, v212
	v_lshlrev_b32_e32 v162, 16, v214
	v_and_b32_e32 v163, 0xffff0000, v214
	v_lshlrev_b32_e32 v164, 16, v215
	v_pk_add_f32 v[44:45], v[50:51], v[44:45]
	v_pk_add_f32 v[48:49], v[48:49], v[160:161]
	v_pk_add_f32 v[42:43], v[42:43], v[164:165]
	v_pk_add_f32 v[40:41], v[40:41], v[162:163]
	v_cvt_pk_bf16_f32 v160, v48, v49
	v_cvt_pk_bf16_f32 v161, v44, v45
	v_add_co_u32_e32 v168, vcc, s62, v146
	v_cvt_pk_bf16_f32 v162, v40, v41
	v_cvt_pk_bf16_f32 v163, v42, v43
	s_nop 0
	v_addc_co_u32_e32 v169, vcc, 0, v147, vcc
	global_store_dwordx4 v[152:153], v[160:163], off
	v_add_co_u32_e32 v170, vcc, s63, v146
	s_waitcnt vmcnt(15)
	v_lshlrev_b32_e32 v50, 16, v216
	v_and_b32_e32 v51, 0xffff0000, v216
	v_lshlrev_b32_e32 v152, 16, v217
	v_and_b32_e32 v153, 0xffff0000, v217
	v_lshlrev_b32_e32 v160, 16, v218
	v_and_b32_e32 v161, 0xffff0000, v218
	v_lshlrev_b32_e32 v162, 16, v219
	v_and_b32_e32 v163, 0xffff0000, v219
	v_pk_add_f32 v[38:39], v[38:39], v[152:153]
	v_pk_add_f32 v[50:51], v[36:37], v[50:51]
	v_pk_add_f32 v[30:31], v[30:31], v[162:163]
	v_pk_add_f32 v[36:37], v[28:29], v[160:161]
	v_cvt_pk_bf16_f32 v160, v50, v51
	v_cvt_pk_bf16_f32 v161, v38, v39
	v_lshl_add_u64 v[152:153], v[146:147], 0, s[22:23]
	v_cvt_pk_bf16_f32 v162, v36, v37
	v_cvt_pk_bf16_f32 v163, v30, v31
	v_addc_co_u32_e32 v171, vcc, 0, v147, vcc
	global_store_dwordx4 v[86:87], v[160:163], off offset:256
	v_lshl_add_u64 v[146:147], v[146:147], 0, s[28:29]
	s_waitcnt vmcnt(15)
	v_lshlrev_b32_e32 v86, 16, v220
	v_and_b32_e32 v87, 0xffff0000, v220
	v_lshlrev_b32_e32 v28, 16, v221
	v_and_b32_e32 v29, 0xffff0000, v221
	v_lshlrev_b32_e32 v160, 16, v222
	v_and_b32_e32 v161, 0xffff0000, v222
	v_lshlrev_b32_e32 v162, 16, v223
	v_and_b32_e32 v163, 0xffff0000, v223
	v_pk_add_f32 v[28:29], v[34:35], v[28:29]
	v_pk_add_f32 v[32:33], v[32:33], v[86:87]
	v_pk_add_f32 v[26:27], v[26:27], v[162:163]
	v_pk_add_f32 v[24:25], v[24:25], v[160:161]
	v_cvt_pk_bf16_f32 v160, v32, v33
	v_cvt_pk_bf16_f32 v161, v28, v29
	s_nop 0
	v_cvt_pk_bf16_f32 v162, v24, v25
	v_cvt_pk_bf16_f32 v163, v26, v27
	s_waitcnt vmcnt(14)
	v_lshlrev_b32_e32 v34, 16, v224
	global_store_dwordx4 v[168:169], v[160:163], off
	v_and_b32_e32 v35, 0xffff0000, v224
	v_lshlrev_b32_e32 v86, 16, v225
	v_and_b32_e32 v87, 0xffff0000, v225
	v_lshlrev_b32_e32 v160, 16, v226
	v_and_b32_e32 v161, 0xffff0000, v226
	v_lshlrev_b32_e32 v162, 16, v227
	v_and_b32_e32 v163, 0xffff0000, v227
	v_pk_add_f32 v[22:23], v[22:23], v[86:87]
	v_pk_add_f32 v[34:35], v[20:21], v[34:35]
	v_pk_add_f32 v[14:15], v[14:15], v[162:163]
	v_pk_add_f32 v[20:21], v[12:13], v[160:161]
	v_cvt_pk_bf16_f32 v160, v34, v35
	v_cvt_pk_bf16_f32 v161, v22, v23
	s_nop 0
	v_cvt_pk_bf16_f32 v162, v20, v21
	v_cvt_pk_bf16_f32 v163, v14, v15
	s_waitcnt vmcnt(14)
	v_lshlrev_b32_e32 v86, 16, v228
	global_store_dwordx4 v[152:153], v[160:163], off offset:256
	v_and_b32_e32 v87, 0xffff0000, v228
	v_lshlrev_b32_e32 v12, 16, v229
	v_and_b32_e32 v13, 0xffff0000, v229
	v_lshlrev_b32_e32 v152, 16, v230
	v_and_b32_e32 v153, 0xffff0000, v230
	v_lshlrev_b32_e32 v160, 16, v231
	v_and_b32_e32 v161, 0xffff0000, v231
	v_pk_add_f32 v[12:13], v[18:19], v[12:13]
	v_pk_add_f32 v[16:17], v[16:17], v[86:87]
	v_pk_add_f32 v[10:11], v[10:11], v[160:161]
	v_pk_add_f32 v[8:9], v[8:9], v[152:153]
	v_cvt_pk_bf16_f32 v160, v16, v17
	v_cvt_pk_bf16_f32 v161, v12, v13
	v_mul_f32_e32 v18, v125, v125
	v_cvt_pk_bf16_f32 v162, v8, v9
	v_cvt_pk_bf16_f32 v163, v10, v11
	v_mul_f32_e32 v19, v127, v127
	v_mul_f32_e32 v86, v121, v121
	v_mul_f32_e32 v87, v123, v123
	v_fmac_f32_e32 v18, v124, v124
	v_fmac_f32_e32 v19, v126, v126
	v_fmac_f32_e32 v86, v120, v120
	v_fmac_f32_e32 v87, v122, v122
	v_add_f32_e32 v18, v18, v19
	v_add_f32_e32 v19, v86, v87
	v_add_f32_e32 v18, v18, v19
	v_mul_f32_e32 v19, v149, v149
	v_mul_f32_e32 v86, v115, v115
	v_mul_f32_e32 v87, v151, v151
	v_fmac_f32_e32 v19, v148, v148
	v_fmac_f32_e32 v86, v114, v114
	v_fmac_f32_e32 v87, v150, v150
	v_add_f32_e32 v19, v19, v86
	v_add_f32_e32 v86, v87, v113
	v_add_f32_e32 v19, v19, v86
	v_add_f32_e32 v18, v18, v19
	v_mov_b32_e32 v19, v18
	s_nop 1
	v_permlane16_swap_b32_e32 v18, v19
	v_add_f32_e32 v86, v18, v19
	v_mov_b32_e32 v87, v86
	s_nop 1
	v_permlane32_swap_b32_e32 v86, v87
	global_store_dwordx4 v[170:171], v[160:163], off
	s_waitcnt vmcnt(15)
	v_lshlrev_b32_e32 v18, 16, v232
	v_and_b32_e32 v19, 0xffff0000, v232
	v_lshlrev_b32_e32 v112, 16, v233
	v_and_b32_e32 v113, 0xffff0000, v233
	v_lshlrev_b32_e32 v114, 16, v234
	v_and_b32_e32 v115, 0xffff0000, v234
	v_lshlrev_b32_e32 v120, 16, v235
	v_and_b32_e32 v121, 0xffff0000, v235
	v_pk_add_f32 v[6:7], v[6:7], v[112:113]
	v_pk_add_f32 v[18:19], v[4:5], v[18:19]
	v_pk_add_f32 v[2:3], v[2:3], v[120:121]
	v_pk_add_f32 v[4:5], v[0:1], v[114:115]
	v_lshl_add_u64 v[0:1], v[144:145], 2, s[10:11]
	v_cvt_pk_bf16_f32 v112, v18, v19
	v_cvt_pk_bf16_f32 v113, v6, v7
	v_cvt_pk_bf16_f32 v114, v4, v5
	v_cvt_pk_bf16_f32 v115, v2, v3
	global_store_dwordx4 v[146:147], v[112:115], off offset:256
	s_and_saveexec_b64 s[40:41], s[0:1]
	s_cbranch_execz .LBB0_1384
	v_add_f32_e32 v86, v86, v87
	global_atomic_add_f32 v[0:1], v86, off
